# phase-0 transposes of the gain-scaled weights: 64 serial load-gain/wait/multiply steps replaced by 64 gain loads in flight and the multiplies after one wait
# speedup vs baseline: 1.0276x; 1.0162x over previous
.LBB0_281:
	s_or_b64 exec, exec, s[6:7]
	s_cmp_lg_u64 s[0:1], 0
	s_cselect_b64 s[6:7], -1, 0
	s_cmp_eq_u64 s[0:1], 0
	s_cbranch_scc1 .LBB0_283
	v_lshl_add_u64 v[4:5], v[4:5], 2, s[0:1]
	global_load_dword v104, v[4:5], off

.LBB0_285:
	s_or_b64 exec, exec, s[10:11]
	v_cndmask_b32_e64 v1, 0, 1, s[6:7]
	v_cmp_ne_u32_e64 s[10:11], 1, v1
	s_andn2_b64 vcc, exec, s[6:7]
	v_ashrrev_i32_e32 v1, 31, v0
	s_cbranch_vccnz .LBB0_287
	s_ashr_i32 s5, s4, 31
	v_lshl_add_u64 v[4:5], v[0:1], 0, s[4:5]
	v_lshl_add_u64 v[4:5], v[4:5], 2, s[0:1]
	global_load_dword v105, v[4:5], off offset:16

.LBB0_289:
	s_or_b64 exec, exec, s[28:29]
	s_and_b64 vcc, exec, s[10:11]
	s_cbranch_vccnz .LBB0_291
	s_ashr_i32 s5, s4, 31
	v_lshl_add_u64 v[4:5], v[0:1], 0, s[4:5]
	v_lshl_add_u64 v[4:5], v[4:5], 2, s[0:1]
	global_load_dword v106, v[4:5], off offset:32

.LBB0_293:
	s_or_b64 exec, exec, s[28:29]
	s_and_b64 vcc, exec, s[10:11]
	s_cbranch_vccnz .LBB0_295
	s_ashr_i32 s5, s4, 31
	v_lshl_add_u64 v[4:5], v[0:1], 0, s[4:5]
	v_lshl_add_u64 v[4:5], v[4:5], 2, s[0:1]
	global_load_dword v107, v[4:5], off offset:48

.LBB0_297:
	s_or_b64 exec, exec, s[28:29]
	s_and_b64 vcc, exec, s[10:11]
	s_cbranch_vccnz .LBB0_299
	s_ashr_i32 s5, s4, 31
	v_lshl_add_u64 v[4:5], v[0:1], 0, s[4:5]
	v_lshl_add_u64 v[4:5], v[4:5], 2, s[0:1]
	global_load_dword v108, v[4:5], off offset:64

.LBB0_301:
	s_or_b64 exec, exec, s[28:29]
	s_and_b64 vcc, exec, s[10:11]
	s_cbranch_vccnz .LBB0_303
	s_ashr_i32 s5, s4, 31
	v_lshl_add_u64 v[4:5], v[0:1], 0, s[4:5]
	v_lshl_add_u64 v[4:5], v[4:5], 2, s[0:1]
	global_load_dword v109, v[4:5], off offset:80

.LBB0_305:
	s_or_b64 exec, exec, s[28:29]
	s_and_b64 vcc, exec, s[10:11]
	s_cbranch_vccnz .LBB0_307
	s_ashr_i32 s5, s4, 31
	v_lshl_add_u64 v[4:5], v[0:1], 0, s[4:5]
	v_lshl_add_u64 v[4:5], v[4:5], 2, s[0:1]
	global_load_dword v110, v[4:5], off offset:96

.LBB0_309:
	s_or_b64 exec, exec, s[28:29]
	s_and_b64 vcc, exec, s[10:11]
	s_cbranch_vccnz .LBB0_311
	s_ashr_i32 s5, s4, 31
	v_lshl_add_u64 v[4:5], v[0:1], 0, s[4:5]
	v_lshl_add_u64 v[4:5], v[4:5], 2, s[0:1]
	global_load_dword v111, v[4:5], off offset:112

.LBB0_313:
	s_or_b64 exec, exec, s[28:29]
	s_and_b64 vcc, exec, s[10:11]
	s_cbranch_vccnz .LBB0_315
	s_ashr_i32 s5, s4, 31
	v_lshl_add_u64 v[4:5], v[0:1], 0, s[4:5]
	v_lshl_add_u64 v[4:5], v[4:5], 2, s[0:1]
	global_load_dword v112, v[4:5], off offset:128

.LBB0_317:
	s_or_b64 exec, exec, s[28:29]
	s_and_b64 vcc, exec, s[10:11]
	s_cbranch_vccnz .LBB0_319
	s_ashr_i32 s5, s4, 31
	v_lshl_add_u64 v[4:5], v[0:1], 0, s[4:5]
	v_lshl_add_u64 v[4:5], v[4:5], 2, s[0:1]
	global_load_dword v113, v[4:5], off offset:144

.LBB0_321:
	s_or_b64 exec, exec, s[28:29]
	s_and_b64 vcc, exec, s[10:11]
	s_cbranch_vccnz .LBB0_323
	s_ashr_i32 s5, s4, 31
	v_lshl_add_u64 v[4:5], v[0:1], 0, s[4:5]
	v_lshl_add_u64 v[4:5], v[4:5], 2, s[0:1]
	global_load_dword v114, v[4:5], off offset:160

.LBB0_325:
	s_or_b64 exec, exec, s[28:29]
	s_and_b64 vcc, exec, s[10:11]
	s_cbranch_vccnz .LBB0_327
	s_ashr_i32 s5, s4, 31
	v_lshl_add_u64 v[4:5], v[0:1], 0, s[4:5]
	v_lshl_add_u64 v[4:5], v[4:5], 2, s[0:1]
	global_load_dword v115, v[4:5], off offset:176

.LBB0_329:
	s_or_b64 exec, exec, s[28:29]
	s_and_b64 vcc, exec, s[10:11]
	s_cbranch_vccnz .LBB0_331
	s_ashr_i32 s5, s4, 31
	v_lshl_add_u64 v[4:5], v[0:1], 0, s[4:5]
	v_lshl_add_u64 v[4:5], v[4:5], 2, s[0:1]
	global_load_dword v116, v[4:5], off offset:192

.LBB0_333:
	s_or_b64 exec, exec, s[28:29]
	s_and_b64 vcc, exec, s[10:11]
	s_cbranch_vccnz .LBB0_335
	s_ashr_i32 s5, s4, 31
	v_lshl_add_u64 v[4:5], v[0:1], 0, s[4:5]
	v_lshl_add_u64 v[4:5], v[4:5], 2, s[0:1]
	global_load_dword v117, v[4:5], off offset:208

.LBB0_337:
	s_or_b64 exec, exec, s[28:29]
	s_and_b64 vcc, exec, s[10:11]
	s_cbranch_vccnz .LBB0_339
	s_ashr_i32 s5, s4, 31
	v_lshl_add_u64 v[4:5], v[0:1], 0, s[4:5]
	v_lshl_add_u64 v[4:5], v[4:5], 2, s[0:1]
	global_load_dword v118, v[4:5], off offset:224

.LBB0_341:
	s_or_b64 exec, exec, s[28:29]
	s_and_b64 vcc, exec, s[10:11]
	s_cbranch_vccnz .LBB0_343
	s_ashr_i32 s5, s4, 31
	v_lshl_add_u64 v[2:3], v[0:1], 0, s[4:5]
	v_lshl_add_u64 v[2:3], v[2:3], 2, s[0:1]
	global_load_dword v119, v[2:3], off offset:240

.LBB0_345:
	s_or_b64 exec, exec, s[34:35]
	s_and_b64 vcc, exec, s[10:11]
	s_cbranch_vccnz .LBB0_347
	v_lshl_add_u64 v[4:5], v[4:5], 2, s[0:1]
	global_load_dword v120, v[4:5], off

.LBB0_349:
	s_or_b64 exec, exec, s[34:35]
	s_and_b64 vcc, exec, s[10:11]
	s_cbranch_vccnz .LBB0_351
	s_ashr_i32 s29, s28, 31
	v_lshl_add_u64 v[4:5], s[28:29], 0, v[0:1]
	v_lshl_add_u64 v[4:5], v[4:5], 2, s[0:1]
	global_load_dword v121, v[4:5], off offset:16

.LBB0_353:
	s_or_b64 exec, exec, s[34:35]
	s_and_b64 vcc, exec, s[10:11]
	s_cbranch_vccnz .LBB0_355
	s_ashr_i32 s29, s28, 31
	v_lshl_add_u64 v[4:5], s[28:29], 0, v[0:1]
	v_lshl_add_u64 v[4:5], v[4:5], 2, s[0:1]
	global_load_dword v122, v[4:5], off offset:32

.LBB0_357:
	s_or_b64 exec, exec, s[34:35]
	s_and_b64 vcc, exec, s[10:11]
	s_cbranch_vccnz .LBB0_359
	s_ashr_i32 s29, s28, 31
	v_lshl_add_u64 v[4:5], s[28:29], 0, v[0:1]
	v_lshl_add_u64 v[4:5], v[4:5], 2, s[0:1]
	global_load_dword v123, v[4:5], off offset:48

.LBB0_361:
	s_or_b64 exec, exec, s[34:35]
	s_and_b64 vcc, exec, s[10:11]
	s_cbranch_vccnz .LBB0_363
	s_ashr_i32 s29, s28, 31
	v_lshl_add_u64 v[4:5], s[28:29], 0, v[0:1]
	v_lshl_add_u64 v[4:5], v[4:5], 2, s[0:1]
	global_load_dword v124, v[4:5], off offset:64

.LBB0_365:
	s_or_b64 exec, exec, s[34:35]
	s_and_b64 vcc, exec, s[10:11]
	s_cbranch_vccnz .LBB0_367
	s_ashr_i32 s29, s28, 31
	v_lshl_add_u64 v[4:5], s[28:29], 0, v[0:1]
	v_lshl_add_u64 v[4:5], v[4:5], 2, s[0:1]
	global_load_dword v125, v[4:5], off offset:80

.LBB0_369:
	s_or_b64 exec, exec, s[34:35]
	s_and_b64 vcc, exec, s[10:11]
	s_cbranch_vccnz .LBB0_371
	s_ashr_i32 s29, s28, 31
	v_lshl_add_u64 v[4:5], s[28:29], 0, v[0:1]
	v_lshl_add_u64 v[4:5], v[4:5], 2, s[0:1]
	global_load_dword v126, v[4:5], off offset:96

.LBB0_373:
	s_or_b64 exec, exec, s[34:35]
	s_and_b64 vcc, exec, s[10:11]
	s_cbranch_vccnz .LBB0_375
	s_ashr_i32 s29, s28, 31
	v_lshl_add_u64 v[4:5], s[28:29], 0, v[0:1]
	v_lshl_add_u64 v[4:5], v[4:5], 2, s[0:1]
	global_load_dword v127, v[4:5], off offset:112

.LBB0_377:
	s_or_b64 exec, exec, s[34:35]
	s_and_b64 vcc, exec, s[10:11]
	s_cbranch_vccnz .LBB0_379
	s_ashr_i32 s29, s28, 31
	v_lshl_add_u64 v[4:5], s[28:29], 0, v[0:1]
	v_lshl_add_u64 v[4:5], v[4:5], 2, s[0:1]
	global_load_dword v128, v[4:5], off offset:128

.LBB0_381:
	s_or_b64 exec, exec, s[34:35]
	s_and_b64 vcc, exec, s[10:11]
	s_cbranch_vccnz .LBB0_383
	s_ashr_i32 s29, s28, 31
	v_lshl_add_u64 v[4:5], s[28:29], 0, v[0:1]
	v_lshl_add_u64 v[4:5], v[4:5], 2, s[0:1]
	global_load_dword v129, v[4:5], off offset:144

.LBB0_385:
	s_or_b64 exec, exec, s[34:35]
	s_and_b64 vcc, exec, s[10:11]
	s_cbranch_vccnz .LBB0_387
	s_ashr_i32 s29, s28, 31
	v_lshl_add_u64 v[4:5], s[28:29], 0, v[0:1]
	v_lshl_add_u64 v[4:5], v[4:5], 2, s[0:1]
	global_load_dword v130, v[4:5], off offset:160

.LBB0_389:
	s_or_b64 exec, exec, s[34:35]
	s_and_b64 vcc, exec, s[10:11]
	s_cbranch_vccnz .LBB0_391
	s_ashr_i32 s29, s28, 31
	v_lshl_add_u64 v[4:5], s[28:29], 0, v[0:1]
	v_lshl_add_u64 v[4:5], v[4:5], 2, s[0:1]
	global_load_dword v131, v[4:5], off offset:176

.LBB0_393:
	s_or_b64 exec, exec, s[34:35]
	s_and_b64 vcc, exec, s[10:11]
	s_cbranch_vccnz .LBB0_395
	s_ashr_i32 s29, s28, 31
	v_lshl_add_u64 v[4:5], s[28:29], 0, v[0:1]
	v_lshl_add_u64 v[4:5], v[4:5], 2, s[0:1]
	global_load_dword v132, v[4:5], off offset:192

.LBB0_397:
	s_or_b64 exec, exec, s[34:35]
	s_and_b64 vcc, exec, s[10:11]
	s_cbranch_vccnz .LBB0_399
	s_ashr_i32 s29, s28, 31
	v_lshl_add_u64 v[4:5], s[28:29], 0, v[0:1]
	v_lshl_add_u64 v[4:5], v[4:5], 2, s[0:1]
	global_load_dword v133, v[4:5], off offset:208

.LBB0_401:
	s_or_b64 exec, exec, s[34:35]
	s_and_b64 vcc, exec, s[10:11]
	s_cbranch_vccnz .LBB0_403
	s_ashr_i32 s29, s28, 31
	v_lshl_add_u64 v[4:5], s[28:29], 0, v[0:1]
	v_lshl_add_u64 v[4:5], v[4:5], 2, s[0:1]
	global_load_dword v134, v[4:5], off offset:224

.LBB0_405:
	s_or_b64 exec, exec, s[34:35]
	s_and_b64 vcc, exec, s[10:11]
	s_cbranch_vccnz .LBB0_407
	s_ashr_i32 s29, s28, 31
	v_lshl_add_u64 v[2:3], s[28:29], 0, v[0:1]
	v_lshl_add_u64 v[2:3], v[2:3], 2, s[0:1]
	global_load_dword v135, v[2:3], off offset:240

.LBB0_409:
	s_or_b64 exec, exec, s[36:37]
	s_and_b64 vcc, exec, s[10:11]
	s_cbranch_vccnz .LBB0_411
	v_lshl_add_u64 v[4:5], v[4:5], 2, s[0:1]
	global_load_dword v136, v[4:5], off

.LBB0_413:
	s_or_b64 exec, exec, s[36:37]
	s_and_b64 vcc, exec, s[10:11]
	s_cbranch_vccnz .LBB0_415
	s_ashr_i32 s35, s34, 31
	v_lshl_add_u64 v[4:5], s[34:35], 0, v[0:1]
	v_lshl_add_u64 v[4:5], v[4:5], 2, s[0:1]
	global_load_dword v137, v[4:5], off offset:16

.LBB0_417:
	s_or_b64 exec, exec, s[36:37]
	s_and_b64 vcc, exec, s[10:11]
	s_cbranch_vccnz .LBB0_419
	s_ashr_i32 s35, s34, 31
	v_lshl_add_u64 v[4:5], s[34:35], 0, v[0:1]
	v_lshl_add_u64 v[4:5], v[4:5], 2, s[0:1]
	global_load_dword v138, v[4:5], off offset:32

.LBB0_421:
	s_or_b64 exec, exec, s[36:37]
	s_and_b64 vcc, exec, s[10:11]
	s_cbranch_vccnz .LBB0_423
	s_ashr_i32 s35, s34, 31
	v_lshl_add_u64 v[4:5], s[34:35], 0, v[0:1]
	v_lshl_add_u64 v[4:5], v[4:5], 2, s[0:1]
	global_load_dword v139, v[4:5], off offset:48

.LBB0_425:
	s_or_b64 exec, exec, s[36:37]
	s_and_b64 vcc, exec, s[10:11]
	s_cbranch_vccnz .LBB0_427
	s_ashr_i32 s35, s34, 31
	v_lshl_add_u64 v[4:5], s[34:35], 0, v[0:1]
	v_lshl_add_u64 v[4:5], v[4:5], 2, s[0:1]
	global_load_dword v140, v[4:5], off offset:64

.LBB0_429:
	s_or_b64 exec, exec, s[36:37]
	s_and_b64 vcc, exec, s[10:11]
	s_cbranch_vccnz .LBB0_431
	s_ashr_i32 s35, s34, 31
	v_lshl_add_u64 v[4:5], s[34:35], 0, v[0:1]
	v_lshl_add_u64 v[4:5], v[4:5], 2, s[0:1]
	global_load_dword v141, v[4:5], off offset:80

.LBB0_433:
	s_or_b64 exec, exec, s[36:37]
	s_and_b64 vcc, exec, s[10:11]
	s_cbranch_vccnz .LBB0_435
	s_ashr_i32 s35, s34, 31
	v_lshl_add_u64 v[4:5], s[34:35], 0, v[0:1]
	v_lshl_add_u64 v[4:5], v[4:5], 2, s[0:1]
	global_load_dword v142, v[4:5], off offset:96

.LBB0_437:
	s_or_b64 exec, exec, s[36:37]
	s_and_b64 vcc, exec, s[10:11]
	s_cbranch_vccnz .LBB0_439
	s_ashr_i32 s35, s34, 31
	v_lshl_add_u64 v[4:5], s[34:35], 0, v[0:1]
	v_lshl_add_u64 v[4:5], v[4:5], 2, s[0:1]
	global_load_dword v143, v[4:5], off offset:112

.LBB0_441:
	s_or_b64 exec, exec, s[36:37]
	s_and_b64 vcc, exec, s[10:11]
	s_cbranch_vccnz .LBB0_443
	s_ashr_i32 s35, s34, 31
	v_lshl_add_u64 v[4:5], s[34:35], 0, v[0:1]
	v_lshl_add_u64 v[4:5], v[4:5], 2, s[0:1]
	global_load_dword v144, v[4:5], off offset:128

.LBB0_445:
	s_or_b64 exec, exec, s[36:37]
	s_and_b64 vcc, exec, s[10:11]
	s_cbranch_vccnz .LBB0_447
	s_ashr_i32 s35, s34, 31
	v_lshl_add_u64 v[4:5], s[34:35], 0, v[0:1]
	v_lshl_add_u64 v[4:5], v[4:5], 2, s[0:1]
	global_load_dword v145, v[4:5], off offset:144

.LBB0_449:
	s_or_b64 exec, exec, s[36:37]
	s_and_b64 vcc, exec, s[10:11]
	s_cbranch_vccnz .LBB0_451
	s_ashr_i32 s35, s34, 31
	v_lshl_add_u64 v[4:5], s[34:35], 0, v[0:1]
	v_lshl_add_u64 v[4:5], v[4:5], 2, s[0:1]
	global_load_dword v146, v[4:5], off offset:160

.LBB0_453:
	s_or_b64 exec, exec, s[36:37]
	s_and_b64 vcc, exec, s[10:11]
	s_cbranch_vccnz .LBB0_455
	s_ashr_i32 s35, s34, 31
	v_lshl_add_u64 v[4:5], s[34:35], 0, v[0:1]
	v_lshl_add_u64 v[4:5], v[4:5], 2, s[0:1]
	global_load_dword v147, v[4:5], off offset:176

.LBB0_457:
	s_or_b64 exec, exec, s[36:37]
	s_and_b64 vcc, exec, s[10:11]
	s_cbranch_vccnz .LBB0_459
	s_ashr_i32 s35, s34, 31
	v_lshl_add_u64 v[4:5], s[34:35], 0, v[0:1]
	v_lshl_add_u64 v[4:5], v[4:5], 2, s[0:1]
	global_load_dword v148, v[4:5], off offset:192

.LBB0_461:
	s_or_b64 exec, exec, s[36:37]
	s_and_b64 vcc, exec, s[10:11]
	s_cbranch_vccnz .LBB0_463
	s_ashr_i32 s35, s34, 31
	v_lshl_add_u64 v[4:5], s[34:35], 0, v[0:1]
	v_lshl_add_u64 v[4:5], v[4:5], 2, s[0:1]
	global_load_dword v149, v[4:5], off offset:208

.LBB0_465:
	s_or_b64 exec, exec, s[36:37]
	s_and_b64 vcc, exec, s[10:11]
	s_cbranch_vccnz .LBB0_467
	s_ashr_i32 s35, s34, 31
	v_lshl_add_u64 v[4:5], s[34:35], 0, v[0:1]
	v_lshl_add_u64 v[4:5], v[4:5], 2, s[0:1]
	global_load_dword v150, v[4:5], off offset:224

.LBB0_469:
	s_or_b64 exec, exec, s[36:37]
	s_and_b64 vcc, exec, s[10:11]
	s_cbranch_vccnz .LBB0_471
	s_ashr_i32 s35, s34, 31
	v_lshl_add_u64 v[2:3], s[34:35], 0, v[0:1]
	v_lshl_add_u64 v[2:3], v[2:3], 2, s[0:1]
	global_load_dword v151, v[2:3], off offset:240

.LBB0_473:
	s_or_b64 exec, exec, s[30:31]
	s_and_b64 vcc, exec, s[10:11]
	s_cbranch_vccnz .LBB0_475
	v_lshl_add_u64 v[4:5], v[4:5], 2, s[0:1]
	global_load_dword v152, v[4:5], off

.LBB0_477:
	s_or_b64 exec, exec, s[30:31]
	s_and_b64 vcc, exec, s[10:11]
	s_cbranch_vccnz .LBB0_479
	s_ashr_i32 s37, s36, 31
	v_lshl_add_u64 v[92:93], s[36:37], 0, v[0:1]
	v_lshl_add_u64 v[92:93], v[92:93], 2, s[0:1]
	global_load_dword v153, v[92:93], off offset:16

.LBB0_481:
	s_or_b64 exec, exec, s[30:31]
	s_and_b64 vcc, exec, s[10:11]
	s_cbranch_vccnz .LBB0_483
	s_ashr_i32 s37, s36, 31
	v_lshl_add_u64 v[92:93], s[36:37], 0, v[0:1]
	v_lshl_add_u64 v[92:93], v[92:93], 2, s[0:1]
	global_load_dword v154, v[92:93], off offset:32

.LBB0_485:
	s_or_b64 exec, exec, s[30:31]
	s_and_b64 vcc, exec, s[10:11]
	s_cbranch_vccnz .LBB0_487
	s_ashr_i32 s37, s36, 31
	v_lshl_add_u64 v[26:27], s[36:37], 0, v[0:1]
	v_lshl_add_u64 v[26:27], v[26:27], 2, s[0:1]
	global_load_dword v155, v[26:27], off offset:48

.LBB0_489:
	s_or_b64 exec, exec, s[30:31]
	s_and_b64 vcc, exec, s[10:11]
	s_cbranch_vccnz .LBB0_491
	s_ashr_i32 s37, s36, 31
	v_lshl_add_u64 v[92:93], s[36:37], 0, v[0:1]
	v_lshl_add_u64 v[92:93], v[92:93], 2, s[0:1]
	global_load_dword v156, v[92:93], off offset:64

.LBB0_493:
	s_or_b64 exec, exec, s[30:31]
	s_and_b64 vcc, exec, s[10:11]
	s_cbranch_vccnz .LBB0_495
	s_ashr_i32 s37, s36, 31
	v_lshl_add_u64 v[28:29], s[36:37], 0, v[0:1]
	v_lshl_add_u64 v[28:29], v[28:29], 2, s[0:1]
	global_load_dword v157, v[28:29], off offset:80

.LBB0_497:
	s_or_b64 exec, exec, s[30:31]
	s_and_b64 vcc, exec, s[10:11]
	s_cbranch_vccnz .LBB0_499
	s_ashr_i32 s37, s36, 31
	v_lshl_add_u64 v[92:93], s[36:37], 0, v[0:1]
	v_lshl_add_u64 v[92:93], v[92:93], 2, s[0:1]
	global_load_dword v158, v[92:93], off offset:96

.LBB0_501:
	s_or_b64 exec, exec, s[30:31]
	s_and_b64 vcc, exec, s[10:11]
	s_cbranch_vccnz .LBB0_503
	s_ashr_i32 s37, s36, 31
	v_lshl_add_u64 v[30:31], s[36:37], 0, v[0:1]
	v_lshl_add_u64 v[30:31], v[30:31], 2, s[0:1]
	global_load_dword v159, v[30:31], off offset:112

.LBB0_505:
	s_or_b64 exec, exec, s[30:31]
	s_and_b64 vcc, exec, s[10:11]
	s_cbranch_vccnz .LBB0_507
	s_ashr_i32 s37, s36, 31
	v_lshl_add_u64 v[92:93], s[36:37], 0, v[0:1]
	v_lshl_add_u64 v[92:93], v[92:93], 2, s[0:1]
	global_load_dword v160, v[92:93], off offset:128

.LBB0_509:
	s_or_b64 exec, exec, s[30:31]
	s_and_b64 vcc, exec, s[10:11]
	s_cbranch_vccnz .LBB0_511
	s_ashr_i32 s37, s36, 31
	v_lshl_add_u64 v[32:33], s[36:37], 0, v[0:1]
	v_lshl_add_u64 v[32:33], v[32:33], 2, s[0:1]
	global_load_dword v161, v[32:33], off offset:144

.LBB0_513:
	s_or_b64 exec, exec, s[30:31]
	s_and_b64 vcc, exec, s[10:11]
	s_cbranch_vccnz .LBB0_515
	s_ashr_i32 s37, s36, 31
	v_lshl_add_u64 v[92:93], s[36:37], 0, v[0:1]
	v_lshl_add_u64 v[92:93], v[92:93], 2, s[0:1]
	global_load_dword v162, v[92:93], off offset:160

.LBB0_517:
	s_or_b64 exec, exec, s[30:31]
	s_and_b64 vcc, exec, s[10:11]
	s_cbranch_vccnz .LBB0_519
	s_ashr_i32 s37, s36, 31
	v_lshl_add_u64 v[34:35], s[36:37], 0, v[0:1]
	v_lshl_add_u64 v[34:35], v[34:35], 2, s[0:1]
	global_load_dword v163, v[34:35], off offset:176

.LBB0_521:
	s_or_b64 exec, exec, s[30:31]
	s_and_b64 vcc, exec, s[10:11]
	s_cbranch_vccnz .LBB0_523
	s_ashr_i32 s37, s36, 31
	v_lshl_add_u64 v[92:93], s[36:37], 0, v[0:1]
	v_lshl_add_u64 v[92:93], v[92:93], 2, s[0:1]
	global_load_dword v164, v[92:93], off offset:192

.LBB0_525:
	s_or_b64 exec, exec, s[30:31]
	s_and_b64 vcc, exec, s[10:11]
	s_cbranch_vccnz .LBB0_527
	s_ashr_i32 s37, s36, 31
	v_lshl_add_u64 v[92:93], s[36:37], 0, v[0:1]
	v_lshl_add_u64 v[92:93], v[92:93], 2, s[0:1]
	global_load_dword v165, v[92:93], off offset:208

.LBB0_529:
	s_or_b64 exec, exec, s[30:31]
	s_and_b64 vcc, exec, s[10:11]
	s_cbranch_vccnz .LBB0_531
	s_ashr_i32 s37, s36, 31
	v_lshl_add_u64 v[38:39], s[36:37], 0, v[0:1]
	v_lshl_add_u64 v[38:39], v[38:39], 2, s[0:1]
	global_load_dword v166, v[38:39], off offset:224

.LBB0_533:
	s_or_b64 exec, exec, s[10:11]
	s_and_b64 vcc, exec, s[6:7]
	s_cbranch_vccz .LBB0_535
	s_ashr_i32 s37, s36, 31
	v_lshl_add_u64 v[2:3], s[36:37], 0, v[0:1]
	v_lshl_add_u64 v[2:3], v[2:3], 2, s[0:1]
	global_load_dword v167, v[2:3], off offset:240
	s_waitcnt vmcnt(0)
	v_mul_f32_e32 v8, v8, v104
	v_mul_f32_e32 v9, v9, v105
	v_mul_f32_e32 v10, v10, v106
	v_mul_f32_e32 v11, v11, v107
	v_mul_f32_e32 v12, v12, v108
	v_mul_f32_e32 v13, v13, v109
	v_mul_f32_e32 v14, v14, v110
	v_mul_f32_e32 v15, v15, v111
	v_mul_f32_e32 v16, v16, v112
	v_mul_f32_e32 v17, v17, v113
	v_mul_f32_e32 v18, v18, v114
	v_mul_f32_e32 v19, v19, v115
	v_mul_f32_e32 v20, v20, v116
	v_mul_f32_e32 v21, v21, v117
	v_mul_f32_e32 v22, v22, v118
	v_mul_f32_e32 v23, v23, v119
	v_mul_f32_e32 v24, v24, v120
	v_mul_f32_e32 v40, v40, v121
	v_mul_f32_e32 v41, v41, v122
	v_mul_f32_e32 v42, v42, v123
	v_mul_f32_e32 v43, v43, v124
	v_mul_f32_e32 v44, v44, v125
	v_mul_f32_e32 v45, v45, v126
	v_mul_f32_e32 v46, v46, v127
	v_mul_f32_e32 v47, v47, v128
	v_mul_f32_e32 v48, v48, v129
	v_mul_f32_e32 v49, v49, v130
	v_mul_f32_e32 v50, v50, v131
	v_mul_f32_e32 v51, v51, v132
	v_mul_f32_e32 v52, v52, v133
	v_mul_f32_e32 v53, v53, v134
	v_mul_f32_e32 v54, v54, v135
	v_mul_f32_e32 v55, v55, v136
	v_mul_f32_e32 v56, v56, v137
	v_mul_f32_e32 v57, v57, v138
	v_mul_f32_e32 v58, v58, v139
	v_mul_f32_e32 v59, v59, v140
	v_mul_f32_e32 v60, v60, v141
	v_mul_f32_e32 v61, v61, v142
	v_mul_f32_e32 v62, v62, v143
	v_mul_f32_e32 v63, v63, v144
	v_mul_f32_e32 v80, v80, v145
	v_mul_f32_e32 v81, v81, v146
	v_mul_f32_e32 v82, v82, v147
	v_mul_f32_e32 v83, v83, v148
	v_mul_f32_e32 v84, v84, v149
	v_mul_f32_e32 v85, v85, v150
	v_mul_f32_e32 v86, v86, v151
	v_mul_f32_e32 v87, v87, v152
	v_mul_f32_e32 v4, v4, v153
	v_mul_f32_e32 v5, v5, v154
	v_mul_f32_e32 v25, v25, v155
	v_mul_f32_e32 v26, v26, v156
	v_mul_f32_e32 v27, v27, v157
	v_mul_f32_e32 v28, v28, v158
	v_mul_f32_e32 v29, v29, v159
	v_mul_f32_e32 v30, v30, v160
	v_mul_f32_e32 v31, v31, v161
	v_mul_f32_e32 v32, v32, v162
	v_mul_f32_e32 v33, v33, v163
	v_mul_f32_e32 v34, v34, v164
	v_mul_f32_e32 v35, v35, v165
	v_mul_f32_e32 v37, v37, v166
	v_mul_f32_e32 v1, v38, v167
	s_cbranch_execnz .LBB0_253
	s_branch .LBB0_536
